# group B: V prefetch at top of softmax, P0 cvt before barrier, DMA issue interleaved after first PV MFMAs
# speedup vs baseline: 1.0771x; 1.0313x over previous
; DI int crow(int i, int hh) { return (i & 3) + 8 * (i >> 2) + 4 * hh; }
; #define LAS __attribute__((address_space(3)))
; DI void diff_core(unsigned char* smem, const u16* qptr, const u16* kbase, const u16* vtbase, int vld,
;                   int ntb, int ntw, int nvalid, int ks0, const float* lut, int qpos, bool active, bool grpB,
;                   f32x16 (&O)[4], float& l_out) {
;     ...
;   auto pv = [&](int slot) {
;     if (grpB) __builtin_amdgcn_s_setprio(2); else __builtin_amdgcn_s_setprio(1);
;     const LAS unsigned char* b = lds + slot * D_SLOT;
;     bf16x8 va[4], vb[4];
; #pragma unroll
;     for (int tt = 0; tt < 4; ++tt) va[tt] = *reinterpret_cast<const LAS bf16x8*>(b + voff[0] + tt * 32 * 128);
; #pragma unroll
;     for (int tt = 0; tt < 4; ++tt) vb[tt] = *reinterpret_cast<const LAS bf16x8*>(b + voff[1] + tt * 32 * 128);
;     ...
;     if (lut != nullptr && t >= ntw - 3) {
;       const int base = t * 64 - qpos + 191;
; #pragma unroll
;       for (int kb = 0; kb < 2; ++kb)
; #pragma unroll
;         for (int i = 0; i < 16; ++i) S[kb][i] += lut[base + kb * 32 + crow(i, hh)];
;     }
.LBB0_378:
	s_add_i32 s64, s62, 0x101
	s_add_i32 s65, s62, 0x104
	s_min_i32 s65, s65, s58
	s_add_i32 s66, s59, 0x8000
	s_and_b32 s66, s66, 0x18000
	s_add_i32 s85, s6, s66
	s_lshl_b32 s66, s65, 6
	s_ashr_i32 s67, s66, 31
	s_lshl_b64 s[86:87], s[66:67], 11
	s_add_u32 s86, s14, s86
	s_addc_u32 s87, s15, s87
	s_lshl_b64 s[66:67], s[66:67], 1
	s_add_i32 s65, s85, 0x2000
	s_add_u32 s66, s20, s66
	s_addc_u32 s67, s21, s67
	s_add_i32 s88, s85, 0x4000
	s_add_i32 s89, s85, 0x6000
	s_cmp_lt_u32 s64, s16
	s_cselect_b64 s[0:1], -1, 0
	s_cmp_ge_u32 s64, s16
	s_cbranch_scc1 .LBB0_384
	s_add_i32 s100, s59, 0xffff0000
	s_and_b32 s100, s100, 0x18000
	v_add_u32_e32 v248, s100, v188
	ds_read_b128 v[200:203], v248 offset:16384
	ds_read_b128 v[204:207], v248 offset:20480
	ds_read_b128 v[208:211], v248 offset:24576
	ds_read_b128 v[212:215], v248 offset:28672
	v_add_u32_e32 v249, s100, v187
	ds_read_b128 v[216:219], v249 offset:16384
	ds_read_b128 v[220:223], v249 offset:20480
	ds_read_b128 v[224:227], v249 offset:24576
	ds_read_b128 v[228:231], v249 offset:28672
	s_cmp_lt_i32 s64, s17
	s_cbranch_scc1 .LBB0_381
	ds_read2_b32 v[98:99], v96 offset1:1
	ds_read2_b32 v[100:101], v96 offset0:16 offset1:17
	ds_read2_b32 v[102:103], v96 offset0:18 offset1:19
	ds_read2_b32 v[104:105], v96 offset0:24 offset1:25
	ds_read2_b32 v[106:107], v96 offset0:26 offset1:27
	ds_read2_b32 v[108:109], v96 offset0:2 offset1:3
	ds_read2_b32 v[110:111], v96 offset0:8 offset1:9
	ds_read2_b32 v[112:113], v96 offset0:10 offset1:11
	s_waitcnt lgkmcnt(0)
	v_pk_add_f32 v[80:81], v[80:81], v[98:99]
	v_pk_add_f32 v[94:95], v[94:95], v[106:107]
	v_pk_add_f32 v[92:93], v[92:93], v[104:105]
	v_pk_add_f32 v[90:91], v[90:91], v[102:103]
	v_pk_add_f32 v[88:89], v[88:89], v[100:101]
	v_pk_add_f32 v[86:87], v[86:87], v[112:113]
	v_pk_add_f32 v[84:85], v[84:85], v[110:111]
	v_pk_add_f32 v[82:83], v[82:83], v[108:109]
	ds_read2_b32 v[98:99], v96 offset0:32 offset1:33
	ds_read2_b32 v[100:101], v96 offset0:48 offset1:49
	ds_read2_b32 v[102:103], v96 offset0:50 offset1:51
	ds_read2_b32 v[104:105], v96 offset0:56 offset1:57
	ds_read2_b32 v[106:107], v96 offset0:58 offset1:59
	ds_read2_b32 v[108:109], v96 offset0:34 offset1:35
	ds_read2_b32 v[110:111], v96 offset0:40 offset1:41
	ds_read2_b32 v[112:113], v96 offset0:42 offset1:43
	s_waitcnt lgkmcnt(0)
	v_pk_add_f32 v[64:65], v[64:65], v[98:99]
	v_pk_add_f32 v[78:79], v[78:79], v[106:107]
	v_pk_add_f32 v[76:77], v[76:77], v[104:105]
	v_pk_add_f32 v[74:75], v[74:75], v[102:103]
	v_pk_add_f32 v[72:73], v[72:73], v[100:101]
	v_pk_add_f32 v[70:71], v[70:71], v[112:113]
	v_pk_add_f32 v[68:69], v[68:69], v[110:111]
	v_pk_add_f32 v[66:67], v[66:67], v[108:109]

; DI void diff_core(unsigned char* smem, const u16* qptr, const u16* kbase, const u16* vtbase, int vld,
;                   int ntb, int ntw, int nvalid, int ks0, const float* lut, int qpos, bool active, bool grpB,
;                   f32x16 (&O)[4], float& l_out) {
;     ...
;   auto pv = [&](int slot) {
;     if (grpB) __builtin_amdgcn_s_setprio(2); else __builtin_amdgcn_s_setprio(1);
;     const LAS unsigned char* b = lds + slot * D_SLOT;
;     bf16x8 va[4], vb[4];
; #pragma unroll
;     for (int tt = 0; tt < 4; ++tt) va[tt] = *reinterpret_cast<const LAS bf16x8*>(b + voff[0] + tt * 32 * 128);
; #pragma unroll
;     for (int tt = 0; tt < 4; ++tt) vb[tt] = *reinterpret_cast<const LAS bf16x8*>(b + voff[1] + tt * 32 * 128);
;     {
;       const bf16x8 pf = __builtin_bit_cast(bf16x8, P[0]);
; #pragma unroll
;       for (int tt = 0; tt < 4; ++tt) O[tt] = MFMA(va[tt], pf, O[tt]);
;     }
; #pragma unroll
;     for (int tt = 0; tt < 4; ++tt) va[tt] = *reinterpret_cast<const LAS bf16x8*>(b + voff[2] + tt * 32 * 128);
;     {
;       const bf16x8 pf = __builtin_bit_cast(bf16x8, P[1]);
; #pragma unroll
;       for (int tt = 0; tt < 4; ++tt) O[tt] = MFMA(vb[tt], pf, O[tt]);
;     }
; #pragma unroll
;     for (int tt = 0; tt < 4; ++tt) vb[tt] = *reinterpret_cast<const LAS bf16x8*>(b + voff[3] + tt * 32 * 128);
;     {
;       const bf16x8 pf = __builtin_bit_cast(bf16x8, P[2]);
; #pragma unroll
;       for (int tt = 0; tt < 4; ++tt) O[tt] = MFMA(va[tt], pf, O[tt]);
;     }
;     {
;       const bf16x8 pf = __builtin_bit_cast(bf16x8, P[3]);
; #pragma unroll
;       for (int tt = 0; tt < 4; ++tt) O[tt] = MFMA(vb[tt], pf, O[tt]);
;     }
;     __builtin_amdgcn_sched_group_barrier(0x100, 8, 0);
;     __builtin_amdgcn_sched_group_barrier(0x008, 4, 0);
;     __builtin_amdgcn_sched_group_barrier(0x100, 4, 0);
;     __builtin_amdgcn_sched_group_barrier(0x008, 4, 0);
;     __builtin_amdgcn_sched_group_barrier(0x100, 4, 0);
;     __builtin_amdgcn_sched_group_barrier(0x008, 8, 0);
;     __builtin_amdgcn_s_setprio(0);
;   };
;     ...
;     float ps = 0.f;
; #pragma unroll
;     for (int kb = 0; kb < 2; ++kb)
; #pragma unroll
;       for (int i = 0; i < 16; ++i) {
;         const float pe = __builtin_amdgcn_exp2f(S[kb][i]);
;         S[kb][i] = pe;
;         ps += pe;
;       }
;     l += ps;
; #pragma unroll
;     for (int kb = 0; kb < 2; ++kb)
; #pragma unroll
.LBB0_383:
	v_exp_f32_e32 v80, v80
	v_exp_f32_e32 v81, v81
	v_exp_f32_e32 v82, v82
	v_exp_f32_e32 v83, v83
	v_exp_f32_e32 v84, v84
	v_exp_f32_e32 v85, v85
	v_exp_f32_e32 v86, v86
	v_exp_f32_e32 v87, v87
	v_exp_f32_e32 v88, v88
	v_exp_f32_e32 v89, v89
	v_exp_f32_e32 v90, v90
	v_exp_f32_e32 v91, v91
	v_exp_f32_e32 v92, v92
	v_exp_f32_e32 v93, v93
	v_exp_f32_e32 v94, v94
	v_exp_f32_e32 v95, v95
	v_exp_f32_e32 v64, v64
	v_exp_f32_e32 v65, v65
	v_exp_f32_e32 v66, v66
	v_exp_f32_e32 v67, v67
	v_exp_f32_e32 v68, v68
	v_exp_f32_e32 v69, v69
	v_exp_f32_e32 v70, v70
	v_exp_f32_e32 v71, v71
	v_exp_f32_e32 v72, v72
	v_exp_f32_e32 v73, v73
	v_exp_f32_e32 v74, v74
	v_exp_f32_e32 v75, v75
	v_exp_f32_e32 v76, v76
	v_exp_f32_e32 v77, v77
	v_exp_f32_e32 v78, v78
	v_exp_f32_e32 v79, v79
	v_cvt_pk_bf16_f32 v144, v80, v81
	v_cvt_pk_bf16_f32 v145, v82, v83
	v_cvt_pk_bf16_f32 v146, v84, v85
	v_cvt_pk_bf16_f32 v147, v86, v87
	v_add_f32_e32 v250, v81, v80
	v_add_f32_e32 v250, v82, v250
.LBB0_384:
	s_waitcnt vmcnt(4)
	s_barrier
	s_andn2_b64 vcc, exec, s[0:1]
	s_cbranch_vccnz .LB_dma_only
	s_setprio 2
	s_add_i32 s0, s59, 0xffff0000
	s_and_b32 s0, s0, 0x18000
	v_add_u32_e32 v97, s0, v186
	ds_read_b128 v[98:101], v97 offset:16384
	ds_read_b128 v[102:105], v97 offset:20480
	ds_read_b128 v[106:109], v97 offset:24576
	ds_read_b128 v[110:113], v97 offset:28672
	s_add_i32 s101, s59, 0xffff8000
	s_and_b32 s101, s101, 0x18000
	s_waitcnt lgkmcnt(4)
	s_mov_b32 m0, s85
	v_mfma_f32_32x32x16_bf16 v[48:63], v[200:203], v[144:147], v[48:63]
	v_cvt_pk_bf16_f32 v148, v88, v89
	v_add_f32_e32 v250, v83, v250
	v_add_f32_e32 v250, v84, v250
	global_load_lds_dwordx4 v162, s[86:87]
	v_add_u32_e32 v126, s0, v184
	ds_read_b128 v[114:117], v126 offset:16384
	ds_read_b128 v[118:121], v126 offset:20480
	ds_read_b128 v[122:125], v126 offset:24576
	ds_read_b128 v[196:199], v126 offset:28672
	s_mov_b32 m0, s65
	v_mfma_f32_32x32x16_bf16 v[32:47], v[204:207], v[144:147], v[32:47]
	v_cvt_pk_bf16_f32 v149, v90, v91
	v_add_f32_e32 v250, v85, v250
	v_add_f32_e32 v250, v86, v250
	global_load_lds_dwordx4 v170, s[86:87]
	s_mov_b32 m0, s88
	v_mfma_f32_32x32x16_bf16 v[16:31], v[208:211], v[144:147], v[16:31]
	v_cvt_pk_bf16_f32 v150, v92, v93
	v_add_f32_e32 v250, v87, v250
	v_add_f32_e32 v250, v88, v250
	global_load_lds_dwordx4 v166, s[66:67]
	s_mov_b32 m0, s89
	v_mfma_f32_32x32x16_bf16 v[0:15], v[212:215], v[144:147], v[0:15]
	v_cvt_pk_bf16_f32 v151, v94, v95
	v_add_f32_e32 v250, v89, v250
	v_add_f32_e32 v250, v90, v250
	global_load_lds_dwordx4 v168, s[66:67]
	v_mfma_f32_32x32x16_bf16 v[48:63], v[216:219], v[148:151], v[48:63]
	v_cvt_pk_bf16_f32 v152, v64, v65
	v_add_f32_e32 v250, v91, v250
	v_add_f32_e32 v250, v92, v250
	v_mfma_f32_32x32x16_bf16 v[32:47], v[220:223], v[148:151], v[32:47]
	v_cvt_pk_bf16_f32 v153, v66, v67
	v_add_f32_e32 v250, v93, v250
	v_add_f32_e32 v250, v94, v250
	v_mfma_f32_32x32x16_bf16 v[16:31], v[224:227], v[148:151], v[16:31]
	v_cvt_pk_bf16_f32 v154, v68, v69
	v_add_f32_e32 v250, v95, v250
	v_add_f32_e32 v250, v64, v250
	v_mfma_f32_32x32x16_bf16 v[0:15], v[228:231], v[148:151], v[0:15]
	v_cvt_pk_bf16_f32 v155, v70, v71
	v_add_f32_e32 v250, v65, v250
	v_add_f32_e32 v250, v66, v250
	v_add_u32_e32 v97, s101, v177
	ds_read_b128 v[200:203], v97
	ds_read_b128 v[204:207], v97 offset:8192
	v_add_u32_e32 v126, s101, v178
	ds_read_b128 v[208:211], v126
	ds_read_b128 v[212:215], v126 offset:8192
	s_waitcnt lgkmcnt(8)
	v_mfma_f32_32x32x16_bf16 v[48:63], v[98:101], v[152:155], v[48:63]
	v_cvt_pk_bf16_f32 v156, v72, v73
	v_add_f32_e32 v250, v67, v250
	v_add_f32_e32 v250, v68, v250
	v_mfma_f32_32x32x16_bf16 v[32:47], v[102:105], v[152:155], v[32:47]
	v_cvt_pk_bf16_f32 v157, v74, v75
	v_add_f32_e32 v250, v69, v250
	v_add_f32_e32 v250, v70, v250
	v_mfma_f32_32x32x16_bf16 v[16:31], v[106:109], v[152:155], v[16:31]
	v_cvt_pk_bf16_f32 v158, v76, v77
	v_add_f32_e32 v250, v71, v250
	v_add_f32_e32 v250, v72, v250
	v_mfma_f32_32x32x16_bf16 v[0:15], v[110:113], v[152:155], v[0:15]
	v_cvt_pk_bf16_f32 v159, v78, v79
	v_add_f32_e32 v250, v73, v250
	v_add_f32_e32 v250, v74, v250
	v_add_u32_e32 v97, s101, v179
	ds_read_b128 v[216:219], v97
	ds_read_b128 v[220:223], v97 offset:8192
	v_add_u32_e32 v126, s101, v180
	ds_read_b128 v[224:227], v126
	ds_read_b128 v[228:231], v126 offset:8192
	s_waitcnt lgkmcnt(8)
	v_mfma_f32_32x32x16_bf16 v[48:63], v[114:117], v[156:159], v[48:63]
	v_add_f32_e32 v250, v75, v250
	v_add_f32_e32 v250, v76, v250
	v_mfma_f32_32x32x16_bf16 v[32:47], v[118:121], v[156:159], v[32:47]
	v_add_f32_e32 v250, v77, v250
	v_add_f32_e32 v250, v78, v250
	v_mfma_f32_32x32x16_bf16 v[16:31], v[122:125], v[156:159], v[16:31]
	v_add_f32_e32 v250, v79, v250
	v_mfma_f32_32x32x16_bf16 v[0:15], v[196:199], v[156:159], v[0:15]
	v_add_f32_e32 v181, v181, v250
	s_setprio 0

; #define LAS __attribute__((address_space(3)))
; DI void diff_core(unsigned char* smem, const u16* qptr, const u16* kbase, const u16* vtbase, int vld,
;                   int ntb, int ntw, int nvalid, int ks0, const float* lut, int qpos, bool active, bool grpB,
;                   f32x16 (&O)[4], float& l_out) {
;     ...
;   auto dma_piece = [&](int t, int slot, int piece) {
;     LAS unsigned char* b = lds + slot * D_SLOT + w * 1024;
;     const char* kt = (const char*)kbase + (size_t)(64 * t) * kld * 2;
;     const char* vt = (const char*)vtbase + (size_t)(64 * t) * 2;
;     if (piece == 0) __builtin_amdgcn_global_load_lds((const unsigned*)(kt + ksrc[0]), (LAS unsigned*)(b), 16, 0, 0);
;     else if (piece == 1) __builtin_amdgcn_global_load_lds((const unsigned*)(kt + ksrc[1]), (LAS unsigned*)(b + 8192), 16, 0, 0);
;     else if (piece == 2) __builtin_amdgcn_global_load_lds((const unsigned*)(vt + vsrc[0]), (LAS unsigned*)(b + 16384), 16, 0, 0);
;     else __builtin_amdgcn_global_load_lds((const unsigned*)(vt + vsrc[1]), (LAS unsigned*)(b + 24576), 16, 0, 0);
;   };
;   auto dma = [&](int t, int slot) { dma_piece(t, slot, 0); dma_piece(t, slot, 1); dma_piece(t, slot, 2); dma_piece(t, slot, 3); };
.LB_dma_only:
	s_mov_b32 m0, s85
	s_nop 0
	global_load_lds_dwordx4 v162, s[86:87]
	s_mov_b32 m0, s65
	s_nop 0
	global_load_lds_dwordx4 v170, s[86:87]
	s_mov_b32 m0, s88
	s_nop 0
	global_load_lds_dwordx4 v166, s[66:67]
	s_mov_b32 m0, s89
	s_nop 0
	global_load_lds_dwordx4 v168, s[66:67]
	s_branch .LBB0_386

; __global__ void __launch_bounds__(NTHR) fwd_megakernel(Params p) {
;   extern __shared__ __attribute__((aligned(16))) unsigned char smem[];
;   cg::grid_group grid = cg::this_grid();
;   if (gridDim.x == 0x7fffffffu) grid.sync();
;   if (p.mode != 0) return;
;   phase0(p, smem);
	.amdhsa_kernel _Z14fwd_megakernel6Params
		.amdhsa_group_segment_fixed_size 0
		.amdhsa_private_segment_fixed_size 0
		.amdhsa_kernarg_size 584
		.amdhsa_user_sgpr_count 2
		.amdhsa_user_sgpr_dispatch_ptr 0
		.amdhsa_user_sgpr_queue_ptr 0
		.amdhsa_user_sgpr_kernarg_segment_ptr 1
		.amdhsa_user_sgpr_dispatch_id 0
		.amdhsa_user_sgpr_kernarg_preload_length 0
		.amdhsa_user_sgpr_kernarg_preload_offset 0
		.amdhsa_user_sgpr_private_segment_size 0
		.amdhsa_uses_dynamic_stack 0
		.amdhsa_enable_private_segment 0
		.amdhsa_system_sgpr_workgroup_id_x 1
		.amdhsa_system_sgpr_workgroup_id_y 0
		.amdhsa_system_sgpr_workgroup_id_z 0
		.amdhsa_system_sgpr_workgroup_info 0
		.amdhsa_system_vgpr_workitem_id 2
		.amdhsa_next_free_vgpr 256
		.amdhsa_next_free_sgpr 102
		.amdhsa_accum_offset 256
		.amdhsa_reserve_vcc 1
		.amdhsa_float_round_mode_32 0
		.amdhsa_float_round_mode_16_64 0
		.amdhsa_float_denorm_mode_32 3
		.amdhsa_float_denorm_mode_16_64 3
		.amdhsa_dx10_clamp 1
		.amdhsa_ieee_mode 1
		.amdhsa_fp16_overflow 0
		.amdhsa_tg_split 0
		.amdhsa_exception_fp_ieee_invalid_op 0
		.amdhsa_exception_fp_denorm_src 0
		.amdhsa_exception_fp_ieee_div_zero 0
		.amdhsa_exception_fp_ieee_overflow 0
		.amdhsa_exception_fp_ieee_underflow 0
		.amdhsa_exception_fp_ieee_inexact 0
		.amdhsa_exception_int_div_zero 0
	.end_amdhsa_kernel
